# v31 + 32-byte code placement shift (8 s_nop at kernel entry)
# speedup vs baseline: 1.0016x; 1.0016x over previous
; #define LAS __attribute__((address_space(3)))
; __device__ __forceinline__ unsigned xb_add(unsigned* p, unsigned v) { return __hip_atomic_fetch_add(p, v, __ATOMIC_RELAXED, __HIP_MEMORY_SCOPE_AGENT); }
; __device__ __forceinline__ unsigned xb_xcc_id() { return (unsigned)__builtin_amdgcn_s_getreg((3 << 11) | 20) & 0xFu; }
; __device__ __forceinline__ XcdBarrier xcd_barrier_post(unsigned* bar, volatile LAS unsigned* st) {
;   XcdBarrier b; b.bar = bar; b.x = xb_xcc_id(); b.st = st;
;   if (threadIdx.x == 0) (void)xb_add(&bar[XB_XCNT(b.x)], 1u);
;   return b;
; __global__ void __launch_bounds__(NTHR, 2) mega(Params p) {
;   extern __shared__ __attribute__((aligned(16))) unsigned char lds_raw[];
;   cg::grid_group grid = cg::this_grid();
;   LAS unsigned char* lds = (LAS unsigned char*)lds_raw;
;   char* ldsg = (char*)lds_raw;
;   if (threadIdx.x < 4) ((LAS unsigned*)(lds + LDS_BYTES - 16))[threadIdx.x] = 0u;
;   __syncthreads();
;   const XcdBarrier xb = xcd_barrier_post((unsigned*)(p.ws + O_BAR), (volatile LAS unsigned*)(lds + LDS_BYTES - 16));
_Z4mega6Params:
	s_nop 0
	s_nop 0
	s_nop 0
	s_nop 0
	s_nop 0
	s_nop 0
	s_nop 0
	s_nop 0
	s_load_dwordx4 s[80:83], s[0:1], 0xc0
	s_load_dword s34, s[0:1], 0xd0
	s_add_u32 s20, s0, 0xc8
	v_and_b32_e32 v135, 0x3ff, v0
	v_writelane_b32 v253, s2, 0
	s_addc_u32 s21, s1, 0
	v_cmp_gt_u32_e32 vcc, 4, v135
	s_and_saveexec_b64 s[2:3], vcc
	v_lshl_add_u32 v1, v135, 2, 0
	v_add_u32_e32 v1, 0x21ff0, v1
	v_mov_b32_e32 v2, 0
	ds_write_b32 v1, v2
	s_or_b64 exec, exec, s[2:3]
	s_waitcnt lgkmcnt(0)
	s_barrier
	s_add_u32 s2, s80, 0x1f586a00
	s_getreg_b32 s4, hwreg(HW_REG_XCC_ID, 0, 4)
	s_addc_u32 s3, s81, 0
	s_and_b32 s33, s4, 15
	v_cmp_eq_u32_e64 s[6:7], 0, v135
	s_mov_b64 s[4:5], exec
	s_nop 0
	v_writelane_b32 v253, s6, 1
	s_nop 1
	v_writelane_b32 v253, s7, 2
	s_and_b64 s[6:7], s[4:5], s[6:7]
	s_mov_b64 exec, s[6:7]
	s_cbranch_execz .LBB0_5
	s_mov_b64 s[6:7], exec
	v_mbcnt_lo_u32_b32 v1, s6, 0
	v_mbcnt_hi_u32_b32 v1, s7, v1
	v_cmp_eq_u32_e32 vcc, 0, v1
	s_and_b64 s[8:9], exec, vcc
	s_mov_b64 exec, s[8:9]
	s_cbranch_execz .LBB0_5
	s_lshl_b32 s8, s33, 8
	s_bcnt1_i32_b64 s6, s[6:7]
	v_mov_b32_e32 v1, s8
	v_mov_b32_e32 v2, s6
	global_atomic_add v1, v2, s[2:3] offset:1024
